# grid barrier: waiting workgroups poll the top-level arrival counter against its per-barrier target instead of the generation word
# speedup vs baseline: 1.0044x; 1.0044x over previous
.LBB0_874:
	s_or_b64 exec, exec, s[8:9]
	v_cvt_f32_u32_e32 v5, v3
	s_waitcnt vmcnt(0)
	v_readfirstlane_b32 s6, v4
	v_sub_u32_e32 v4, 0, v3
	v_rcp_iflag_f32_e32 v5, v5
	v_add_u32_e32 v6, s6, v0
	v_mul_f32_e32 v5, 0x4f7ffffe, v5
	v_cvt_u32_f32_e32 v5, v5
	v_mul_lo_u32 v0, v4, v5
	v_mul_hi_u32 v0, v5, v0
	v_add_u32_e32 v0, v5, v0
	v_mul_hi_u32 v0, v6, v0
	v_mul_lo_u32 v4, v0, v3
	v_sub_u32_e32 v4, v6, v4
	v_add_u32_e32 v5, 1, v0
	v_cmp_ge_u32_e32 vcc, v4, v3
	s_nop 1
	v_cndmask_b32_e32 v0, v0, v5, vcc
	v_sub_u32_e32 v5, v4, v3
	v_cndmask_b32_e32 v4, v4, v5, vcc
	v_add_u32_e32 v5, 1, v0
	v_cmp_ge_u32_e32 vcc, v4, v3
	v_add_u32_e32 v4, 1, v6
	s_nop 0
	v_cndmask_b32_e32 v0, v0, v5, vcc
	v_mul_lo_u32 v5, v3, v0
	v_add_u32_e32 v3, v5, v3
	v_cmp_ne_u32_e32 vcc, v4, v3
	s_and_saveexec_b64 s[6:7], vcc
	s_xor_b64 s[6:7], exec, s[6:7]
	s_cbranch_execz .LBB0_888
	s_waitcnt lgkmcnt(0)
	v_add_u32_e32 v7, 1, v0
	v_mul_lo_u32 v7, v7, v2
	v_mov_b32_e32 v0, -1
	v_readlane_b32 s10, v252, 49
	v_readlane_b32 s11, v252, 50
	s_nop 4
	global_load_dword v2, v1, s[10:11] sc1
	s_waitcnt vmcnt(0)
	v_sub_u32_e32 v2, v2, v7
	v_ashrrev_i32_e32 v2, 31, v2
	v_cmp_eq_u32_e32 vcc, v2, v0
	s_and_saveexec_b64 s[8:9], vcc
	s_cbranch_execz .LBB0_887
	s_mov_b32 s18, 1
	s_mov_b64 s[12:13], 0
	s_branch .LBB0_878

.LBB0_880:
	global_load_dword v2, v1, s[10:11] sc1
	s_add_i32 s18, s18, 1
	s_mov_b64 s[20:21], -1
	s_waitcnt vmcnt(0)
	v_sub_u32_e32 v2, v2, v7
	v_ashrrev_i32_e32 v2, 31, v2
	v_cmp_ne_u32_e32 vcc, v2, v0
	s_orn2_b64 s[16:17], vcc, exec
	s_branch .LBB0_877
